# post_rows overlapped with mixer tail via per-batch completion counters (wave-0 polling + LDS flag), mixer->post grid barrier removed
# baseline (speedup 1.0000x reference)
; #define LAS __attribute__((address_space(3)))
; __device__ __forceinline__ unsigned xb_add(unsigned* p, unsigned v) { return __hip_atomic_fetch_add(p, v, __ATOMIC_RELAXED, __HIP_MEMORY_SCOPE_AGENT); }
; __device__ __forceinline__ unsigned xb_xcc_id() { return (unsigned)__builtin_amdgcn_s_getreg((3 << 11) | 20) & 0xFu; }
; __device__ __forceinline__ XcdBarrier xcd_barrier_post(unsigned* bar, volatile LAS unsigned* st) {
;     XcdBarrier b; b.bar = bar; b.x = xb_xcc_id(); b.st = st;
;     if (threadIdx.x == 0) (void)xb_add(&bar[XB_XCNT(b.x)], 1u);
;     return b;
; }
; __global__ void __launch_bounds__(512, 2) mega_fwd(Args a) {
;     extern __shared__ __attribute__((aligned(16))) unsigned char lds_raw[];
;     LAS unsigned char* lds = (LAS unsigned char*)lds_raw;
;     cg::grid_group grid = cg::this_grid();
;     if (threadIdx.x < 4) ((LAS unsigned*)(lds + LDS_CTRL + 64))[threadIdx.x] = 0u;
;     __syncthreads();
;     const XcdBarrier xbar = xcd_barrier_post((unsigned*)(a.ws + WS_CTL) + CW_BAR, (volatile LAS unsigned*)(lds + LDS_CTRL + 64));
_Z8mega_fwd4Args:
	s_mov_b64 s[92:93], s[0:1]
	s_mov_b32 s99, -1
	s_load_dwordx4 s[72:75], s[0:1], 0xc0
	s_add_u32 s0, s92, 0xd0
	s_addc_u32 s1, s93, 0
	v_and_b32_e32 v174, 0x3ff, v0
	v_writelane_b32 v254, s0, 0
	v_cmp_gt_u32_e32 vcc, 56, v174
	s_nop 0
	v_writelane_b32 v254, s1, 1
	s_and_saveexec_b64 s[0:1], vcc
	v_lshl_add_u32 v1, v174, 2, 0
	v_add_u32_e32 v1, 0x22320, v1
	v_mov_b32_e32 v2, 0
	ds_write_b32 v1, v2
	s_or_b64 exec, exec, s[0:1]
	s_load_dwordx2 s[0:1], s[92:93], 0xd0
	s_waitcnt lgkmcnt(0)
	s_barrier
	s_getreg_b32 s3, hwreg(HW_REG_XCC_ID, 0, 4)
	v_writelane_b32 v254, s0, 2
	v_cmp_eq_u32_e64 s[6:7], 0, v174
	s_nop 0
	v_writelane_b32 v254, s1, 3
	s_add_u32 s0, s72, 0x1000
	s_addc_u32 s1, s73, 0
	s_and_b32 s10, s3, 15
	s_mov_b64 s[4:5], exec
	v_writelane_b32 v254, s6, 4
	s_nop 1
	v_writelane_b32 v254, s7, 5
	s_and_b64 s[6:7], s[4:5], s[6:7]
	s_mov_b64 exec, s[6:7]
	s_cbranch_execz .LBB0_5
	s_mov_b64 s[6:7], exec
	v_mbcnt_lo_u32_b32 v1, s6, 0
	v_mbcnt_hi_u32_b32 v1, s7, v1
	v_cmp_eq_u32_e32 vcc, 0, v1
	s_and_b64 s[8:9], exec, vcc
	s_mov_b64 exec, s[8:9]
	s_cbranch_execz .LBB0_5
	s_lshl_b32 s3, s10, 8
	s_bcnt1_i32_b64 s6, s[6:7]
	v_mov_b32_e32 v1, s3
	v_mov_b32_e32 v2, s6
	global_atomic_add v1, v2, s[0:1] offset:1024

; __global__ void __launch_bounds__(512, 2) mega_fwd(Args a) {
;     ...
;     for (int ph = ph_lo; ph < ph_hi; ++ph) {
;     ArgP ap = (ArgP)__builtin_amdgcn_kernarg_segment_ptr(); asm volatile("" : "+s"(ap));
;     int tid = threadIdx.x; asm volatile("" : "+v"(tid));
;     int bid = blockIdx.x; asm volatile("" : "+s"(bid));
;     int nbk = gridDim.x; asm volatile("" : "+s"(nbk));
;     unsigned char* ws = ap->ws;
;     unsigned char* wb = ws + WS_W;
;     bf16_t* xn = (bf16_t*)(ws + WS_XN);
;     bf16_t* act = (bf16_t*)(ws + WS_BIG);
;     bf16_t *zA = (bf16_t*)(ws + WS_ZA), *zB = (bf16_t*)(ws + WS_ZB), *zC = (bf16_t*)(ws + WS_ZC), *zG = (bf16_t*)(ws + WS_ZG);
;     float* mF = (float*)(ws + WS_MF); bf16_t* mB = (bf16_t*)(ws + WS_MB);
;     bf16_t *ya = (bf16_t*)(ws + WS_YA), *yb = ya + 512, *yc = ya + 1024, *OP = (bf16_t*)(ws + WS_OP);
;     float* LSE = (float*)(ws + WS_LSE);
;     unsigned* RS = (unsigned*)(ws + WS_RS);
;     const float* x = ap->in[0]; float* out = ap->out;
;         if (ph == NPH - 1) {
;             final_norm_rows(xn, out, ap->in[22], tid, bid, nbk);
.LBB0_11:
	s_mov_b32 s99, -1
	v_readlane_b32 s12, v254, 2
	s_mov_b64 s[0:1], s[92:93]
	v_mov_b32_e32 v187, v174
	s_mov_b32 s11, s2
	s_mov_b32 s10, s12
	s_load_dwordx2 s[60:61], s[0:1], 0xc0
	v_readlane_b32 s13, v254, 3
	s_mov_b64 s[44:45], 0
	s_mov_b64 s[12:13], -1
	s_waitcnt lgkmcnt(0)
	s_add_u32 s38, s60, 0x3800000
	s_addc_u32 s39, s61, 0
	s_cmp_lg_u32 s7, 34
	s_cbranch_scc1 .LBB0_14
	s_and_b64 vcc, exec, s[12:13]
	s_cbranch_vccnz .LBB0_545

; __device__ __forceinline__ void post_rows(const bf16_t* OP, const float* LSE, const bf16_t* zC, bf16_t* yb, bf16_t* yc, const float* hnorm, int tid, int bid, int nbk) {
;     const int lane = tid & 63, wv = tid >> 6;
;     const int gw = bid * 8 + wv, NGW = nbk * 8;
;     for (int r = gw; r < MH; r += NGW) {
;         {
;             const int hb = lane >> 3;
.LBB0_154:
	v_readfirstlane_b32 s98, v3
	s_nop 1
	s_lshr_b32 s98, s98, 11
	s_cmp_eq_u32 s98, s99
	s_cbranch_scc1 .Lpost_go
	s_mov_b32 s99, s98
	s_cmp_gt_u32 s7, 11
	s_cselect_b32 s100, 0x200, 0
	s_cmp_eq_u32 s7, 11
	s_cselect_b32 s101, 0x100, 0
	s_add_i32 s100, s100, s101
	s_cmp_eq_u32 s7, 28
	s_cselect_b32 s101, 0x100, 0
	s_add_i32 s100, s100, s101
	s_add_i32 s100, s100, 0x8000
	s_lshl_b32 s101, s98, 2
	s_add_i32 s100, s100, s101
	v_mov_b32_e32 v252, s100
	s_lshl_b32 s100, s98, 2
	s_add_i32 s100, s100, 0x223e0
	v_mov_b32_e32 v250, s100
	s_or_b32 s98, s7, 0x5eed0000
	v_readfirstlane_b32 s101, v187
	s_mov_b32 s100, 0
	s_nop 0
	s_cmp_lt_u32 s101, 64
	s_cbranch_scc0 .Lpost_lds
.Lpost_spin:
	global_load_dword v251, v252, s[60:61] sc1
	s_waitcnt vmcnt(0)
	v_readfirstlane_b32 s101, v251
	s_nop 1
	s_cmp_ge_u32 s101, 0x68
	s_cbranch_scc1 .Lpost_pub
	s_add_i32 s100, s100, 1
	s_cmp_ge_u32 s100, 0x2000
	s_cbranch_scc1 .Lpost_pub
	s_sleep 8
	s_branch .Lpost_spin
.Lpost_pub:
	v_mov_b32_e32 v251, s98
	ds_write_b32 v250, v251
	s_waitcnt lgkmcnt(0)
	s_branch .Lpost_go
.Lpost_lds:
	ds_read_b32 v251, v250
	s_waitcnt lgkmcnt(0)
	v_readfirstlane_b32 s101, v251
	s_nop 1
	s_cmp_eq_u32 s101, s98
	s_cbranch_scc1 .Lpost_go
	s_add_i32 s100, s100, 1
	s_cmp_ge_u32 s100, 0x8000
	s_cbranch_scc1 .Lpost_go
	s_sleep 4
	s_branch .Lpost_lds

; __global__ void __launch_bounds__(512, 2) mega_fwd(Args a) {
;     ...
;                     for (;;) {
;                         __syncthreads();
;                         if (tid == 0) *shu = (int)atomicAdd(counter, 1u);
;                         __syncthreads();
.LBB0_162:
	s_cmp_lt_i32 s99, 0
	s_cbranch_scc1 .Lcmp_skipw
	s_waitcnt vmcnt(0)
.Lcmp_skipw:
	s_barrier
	s_and_saveexec_b64 s[42:43], s[40:41]
	s_cbranch_execz .LBB0_166
	s_mov_b64 s[46:47], exec
	v_mbcnt_lo_u32_b32 v0, s46, 0
	v_mbcnt_hi_u32_b32 v0, s47, v0
	v_cmp_eq_u32_e32 vcc, 0, v0
	s_and_saveexec_b64 s[44:45], vcc
	s_cbranch_execz .LBB0_165
	s_cmp_lt_i32 s99, 0
	s_cbranch_scc1 .Lcmp_noinc
	s_lshl_b32 s98, s99, 2
	s_add_i32 s98, s98, 0x8000
	v_mov_b32_e32 v250, s98
	v_mov_b32_e32 v251, 1
	global_atomic_add v250, v251, s[68:69]
.Lcmp_noinc:
	s_bcnt1_i32_b64 s14, s[46:47]
	v_mov_b32_e32 v1, s14
	global_atomic_add v1, v2, v1, s[68:69] sc0

; __device__ __forceinline__ void dil_unit(LAS unsigned char* lds, const bf16_t* zB, bf16_t* OP, float* LSE, int bl, int h, int pi, int su, float slope, int tid) {
;     const int lane = tid & 63, wv = __builtin_amdgcn_readfirstlane(tid >> 6), fr = lane & 15, quad = lane >> 4;
;     const int d = (pi == 0) ? 1 : ((pi == 1) ? 4 : 16), L = SEQ / d, nseg = L / 128;
;     const size_t rb = (size_t)bl * SEQ;
; __global__ void __launch_bounds__(512, 2) mega_fwd(Args a) {
;     ...
;                         const int u = *shu;
;                         if (u >= NU_ALL + PROBE_DUP_H * NU_H + PROBE_DUP_A * (NU_D + NU_L)) break;
;                         int tidu = tid; asm volatile("" : "+v"(tidu));
;                         int u2 = u;
;     ...
;                         const bool dummy = u2 < NU_H; if (!dummy) u2 -= NU_H;
;     ...
;                         const bool dummy = false;
;     ...
;                         if (u2 >= NU_ALL) u2 -= (NU_D + NU_L);
;     ...
;                         if (dummy || u2 < NU_H) {
;                             const int dir = u2 & 1, h = (u2 >> 1) & 3, bl = u2 >> 3;
;                             float lb = 0.f;
;                             if (l == 1) { const int k = tidu & 127; const float x0 = ap->in[12][h * 128 + k], x1 = ap->in[12][512 + h * 128 + k]; const float mx = fmaxf(x0, x1); const float e0 = expf(x0 - mx), e1 = expf(x1 - mx); lb = e1 / (e0 + e1); }
;                             if (dummy) hgrn_unit(lds, zC, bl, h, dir, lb, tidu, OP, 1024, dir * 512 + h * 128);
;                             else hgrn_unit(lds, zC, bl, h, dir, lb, tidu, zC, 2560, 512 + dir * 512 + h * 128);
;                         } else if (u2 < NU_H + NU_D) {
;                             const int v = u2 - NU_H, qt = v & 15, h = (v >> 4) & 3, bl = v >> 6;
;                             const float slope = exp2f(-8.0f * (float)(3 * h + 1) / 12.0f);
;                             diff_unit(lds, zA, ya, bl, h, qt, slope, lam, 1.f - lam_init, ap->in[11] + l * 128, tidu);
;                         } else {
;                             const int v = u2 - NU_H - NU_D, s16 = v & 3, t = v >> 2, pi = t % 3, t2 = t / 3, h = t2 & 7, bl = t2 >> 3;
;                             const int aidx = h + 1 + (h >> 1);
;                             const float slope = exp2f(-8.0f * (float)(aidx + 1) / 12.0f);
;                             dil_unit(lds, zB, OP, LSE, bl, h, pi, s16, slope, tidu);
.LBB0_166:
	s_or_b64 exec, exec, s[42:43]
	v_readlane_b32 s14, v255, 17
	s_waitcnt lgkmcnt(0)
	s_barrier
	v_mov_b32_e32 v0, s14
	ds_read_b32 v0, v0
	s_movk_i32 s14, 0x53f
	s_mov_b64 s[42:43], -1
	s_waitcnt lgkmcnt(0)
	v_cmp_lt_i32_e32 vcc, s14, v0
	v_readfirstlane_b32 s74, v0
	s_mov_b32 s99, -1
	s_nop 0
	s_cmp_lt_u32 s74, 64
	s_cbranch_scc0 .Lcmp_notH
	s_lshr_b32 s99, s74, 3
	s_branch .Lcmp_set
.Lcmp_notH:
	s_cmp_lt_u32 s74, 0x240
	s_cbranch_scc1 .Lcmp_set
	s_cmp_lt_u32 s74, 0x540
	s_cbranch_scc0 .Lcmp_set
	s_sub_u32 s99, s74, 0x240
	s_lshr_b32 s99, s99, 5
	s_mul_i32 s99, s99, 0xaaab
	s_lshr_b32 s99, s99, 17
.Lcmp_set:
	s_cbranch_vccnz .LBB0_161
	v_mov_b32_e32 v152, v187
	s_cmp_gt_i32 s74, 63
	s_cbranch_scc0 .LBB0_187
	s_cmpk_gt_u32 s74, 0x23f
	s_cbranch_scc0 .LBB0_182
	s_add_i32 s14, s74, 0xfffffdc0
	s_mul_i32 s30, s14, 0xaaab
	s_lshr_b32 s42, s30, 19
	s_lshr_b32 s15, s14, 2
	s_bfe_u32 s14, s30, 0x30013
	s_bfe_u32 s42, s42, 0x20001
	s_add_i32 s42, s42, s14
	s_lshl_b32 s42, s42, 3
	s_sub_i32 s42, -16, s42
	v_cvt_f32_i32_e32 v0, s42
	s_mul_i32 s42, s15, 0xab
	s_mov_b32 s2, 0x41400000
	s_bfe_u32 s44, s42, 0x70009
	v_div_scale_f32 v1, s[42:43], s2, s2, v0
	v_rcp_f32_e32 v3, v1
	s_mul_i32 s44, s44, 3
	s_sub_i32 s15, s15, s44
	s_and_b32 s46, s15, 0xff
	v_fma_f32 v4, -v1, v3, 1.0
	v_fmac_f32_e32 v3, v4, v3
	v_div_scale_f32 v4, vcc, v0, s2, v0
	v_mul_f32_e32 v5, v4, v3
	v_fma_f32 v6, -v1, v5, v4
	v_fmac_f32_e32 v5, v6, v3
	v_fma_f32 v1, -v1, v5, v4
	v_div_fmas_f32 v1, v1, v3, v5
	v_div_fixup_f32 v38, v1, s2, v0
	s_mov_b32 s2, 0xc2fc0000
	v_cmp_gt_f32_e32 vcc, s2, v38
	s_and_b64 s[42:43], vcc, exec
	v_mov_b32_e32 v0, 0x42800000
	s_cselect_b32 s15, 0xffffffc0, 0
	s_cmp_eq_u32 s46, 1
	v_cndmask_b32_e32 v39, 0, v0, vcc
	s_cselect_b64 s[42:43], -1, 0
	v_mov_b32_e32 v0, 0x41800000
	v_cndmask_b32_e64 v0, v0, 4.0, s[42:43]
	s_and_b64 s[42:43], s[42:43], exec
	s_cselect_b32 s44, 2, 4
	s_cmp_eq_u32 s46, 0
	s_cselect_b64 s[42:43], -1, 0
	v_cndmask_b32_e64 v44, v0, 1.0, s[42:43]
	s_and_b64 s[42:43], s[42:43], exec
	s_cselect_b32 s62, 0, s44
	s_lshr_b32 s85, 16, s62
	s_lshl_b32 s42, s74, 2
	s_and_b32 s75, s42, 12
	s_add_i32 s85, s85, -1
	s_and_b32 s42, s85, s75
	s_lshr_b32 s63, 0x800, s62
	s_lshr_b32 s30, s30, 11
	s_sub_i32 s84, 4, s62
	s_lshl_b32 s50, s42, 7
	s_and_b32 s30, s30, 0x1ff800
	s_lshr_b32 s47, s75, s84
	s_sub_i32 s43, s50, 64
	s_add_i32 s86, s63, -1
	s_lshl_b32 s42, s14, 7
	s_add_u32 s44, s78, s42
	v_lshlrev_b32_e32 v0, 4, v152
	v_ashrrev_i32_e32 v3, 3, v152
	s_waitcnt vmcnt(8)
	v_add_u32_e32 v12, 0x200, v152
	s_addc_u32 s45, s79, 0
	v_and_b32_e32 v36, 0x70, v0
	v_mov_b32_e32 v37, v2
	v_add_u32_e32 v4, s43, v3
	v_ashrrev_i32_e32 v120, 3, v12
	s_waitcnt vmcnt(6)
	v_add_u32_e32 v20, 0x400, v152
	v_lshl_add_u64 v[0:1], s[44:45], 0, v[36:37]
	v_min_i32_e32 v5, s86, v4
	v_cmp_lt_i32_e32 vcc, -1, v4
	v_add_u32_e32 v12, s43, v120
	v_ashrrev_i32_e32 v121, 3, v20
	s_waitcnt vmcnt(4)
	v_add_u32_e32 v28, 0x600, v152
	v_add_f32_e32 v37, v38, v39
	v_cndmask_b32_e32 v4, 0, v5, vcc
	v_min_i32_e32 v13, s86, v12
	v_cmp_lt_i32_e32 vcc, -1, v12
	v_add_u32_e32 v20, s43, v121
	v_ashrrev_i32_e32 v122, 3, v28
	v_exp_f32_e32 v37, v37
	v_cndmask_b32_e32 v12, 0, v13, vcc
	v_min_i32_e32 v21, s86, v20
	v_cmp_lt_i32_e32 vcc, -1, v20
	v_add_u32_e32 v28, s43, v122
	v_min_i32_e32 v29, s86, v28
	v_cndmask_b32_e32 v20, 0, v21, vcc
	v_cmp_lt_i32_e32 vcc, -1, v28
	v_lshlrev_b32_e32 v4, s62, v4
	s_or_b32 s51, s30, s47
	v_cndmask_b32_e32 v28, 0, v29, vcc
	v_lshlrev_b32_e32 v12, s62, v12
	v_lshlrev_b32_e32 v20, s62, v20
	v_lshlrev_b32_e32 v28, s62, v28
	v_ldexp_f32 v37, v37, s15
	v_readfirstlane_b32 s15, v152
	v_add_u32_e32 v4, s51, v4
	v_add_u32_e32 v12, s51, v12
	v_add_u32_e32 v20, s51, v20
	v_add_u32_e32 v28, s51, v28
	s_ashr_i32 s15, s15, 2
	v_mad_u64_u32 v[8:9], s[48:49], v4, s9, v[0:1]
	v_mad_u64_u32 v[16:17], s[48:49], v12, s9, v[0:1]
	v_mad_u64_u32 v[24:25], s[48:49], v20, s9, v[0:1]
	v_mad_u64_u32 v[32:33], s[48:49], v28, s9, v[0:1]
	s_and_b32 s51, s15, -16
	v_and_b32_e32 v45, 15, v152
	s_add_i32 s48, s51, s50
	v_or_b32_e32 v38, s48, v45
	v_lshlrev_b32_e32 v38, s62, v38
	v_add_u32_e32 v38, s47, v38
	v_ashrrev_i32_e32 v39, 31, v38
	v_lshl_add_u64 v[38:39], v[38:39], 0, s[30:31]
	v_mov_b64_e32 v[40:41], s[78:79]
	v_mad_u64_u32 v[40:41], s[48:49], v38, s9, v[40:41]
	s_mov_b32 s43, s31
	v_bfe_u32 v46, v152, 4, 2
	v_mad_i32_i24 v41, v39, s9, v41
	v_lshl_add_u64 v[38:39], v[40:41], 0, s[42:43]
	v_lshlrev_b32_e32 v42, 4, v46
	v_mov_b32_e32 v43, v2
	v_lshl_add_u64 v[38:39], v[38:39], 0, v[42:43]
	global_load_dwordx4 v[4:7], v[8:9], off offset:1024
	s_nop 0
	global_load_dwordx4 v[8:11], v[8:9], off offset:2048
	s_nop 0
	global_load_dwordx4 v[12:15], v[16:17], off offset:1024
	s_nop 0
	global_load_dwordx4 v[16:19], v[16:17], off offset:2048
	s_nop 0
	global_load_dwordx4 v[20:23], v[24:25], off offset:1024
	s_nop 0
	global_load_dwordx4 v[24:27], v[24:25], off offset:2048
	s_nop 0
	global_load_dwordx4 v[28:31], v[32:33], off offset:1024
	s_nop 0
	global_load_dwordx4 v[32:35], v[32:33], off offset:2048
	s_nop 0
	global_load_dwordx4 v[80:83], v[38:39], off
	global_load_dwordx4 v[84:87], v[38:39], off offset:64
	s_movk_i32 s2, 0xa0
	v_add_u32_e32 v36, 0, v36
	v_mul_lo_u32 v38, v3, s2
	v_add_u32_e32 v123, v36, v38
	v_mul_lo_u32 v38, v120, s2
	v_add_u32_e32 v124, v36, v38
	v_mul_lo_u32 v38, v121, s2
	v_add_u32_e32 v125, v36, v38
	v_mul_lo_u32 v38, v122, s2
	v_add_u32_e32 v126, v36, v38
	v_or_b32_e32 v36, 64, v45
	v_lshlrev_b32_e32 v128, 2, v46
	v_sub_u32_e32 v79, v36, v128
	v_subrev_u32_e32 v48, 50, v79
	v_subrev_u32_e32 v50, 51, v79
	v_subrev_u32_e32 v52, 48, v79
	v_cvt_f32_u32_e32 v51, v50
; #define DL_STORE() do { _Pragma("unroll") for (int j = 0; j < 4; ++j) { const int id = tid + j * 512, row = id >> 3, ch = id & 7; \
;             *(LAS u32x4*)(lds + row * DL_STR + ch * 16) = kv_[j]; *(LAS u32x4*)(lds + DL_KB + row * DL_STR + ch * 16) = vv_[j]; } } while (0)
; template <int DVT, int NKB, bool MASKED, bool EDGE = true> ...
;     ...
;             f32x4 acc = {0.f, 0.f, 0.f, 0.f};
;             if (DEAD) { acc = (f32x4){-1e30f, -1e30f, -1e30f, -1e30f}; }
;             else {
; #pragma unroll
;                 for (int j = 0; j < 4; ++j) acc[j] = nslope * __builtin_fabsf(relq - (float)(nb * 32 + t * 16 + j));
; __device__ __forceinline__ void dil_unit(LAS unsigned char* lds, const bf16_t* zB, bf16_t* OP, float* LSE, int bl, int h, int pi, int su, float slope, int tid) {
;     ...
;     DL_LOAD(4 * su);
;     DL_STORE();
;     __syncthreads();
	v_cvt_f32_u32_e32 v50, v48
	v_cvt_f32_u32_e32 v48, v52
	v_add_u32_e32 v52, 0xffffffbf, v79
	v_subrev_u32_e32 v53, 64, v79
	v_add_u32_e32 v54, 0xffffffbd, v79
	v_add_u32_e32 v55, 0xffffffbe, v79
	v_cvt_f32_i32_e32 v52, v52
	v_cvt_f32_i32_e32 v56, v53
	v_cvt_f32_i32_e32 v54, v54
	v_cvt_f32_i32_e32 v57, v55
	v_and_b32_e32 v53, 0x7fffffff, v52
	v_and_b32_e32 v52, 0x7fffffff, v56
	v_and_b32_e32 v55, 0x7fffffff, v54
	v_and_b32_e32 v54, 0x7fffffff, v57
	v_add_u32_e32 v56, 0xffffffaf, v79
	v_add_u32_e32 v57, 0xffffffb0, v79
	v_add_u32_e32 v58, 0xffffffad, v79
	v_add_u32_e32 v59, 0xffffffae, v79
	v_cvt_f32_i32_e32 v56, v56
	v_cvt_f32_i32_e32 v60, v57
	v_cvt_f32_i32_e32 v58, v58
	v_cvt_f32_i32_e32 v61, v59
	v_xor_b32_e32 v57, 0x80000000, v56
	v_xor_b32_e32 v56, 0x80000000, v60
	v_xor_b32_e32 v59, 0x80000000, v58
	v_xor_b32_e32 v58, 0x80000000, v61
	v_add_u32_e32 v60, 0xffffff9f, v79
	v_add_u32_e32 v61, 0xffffffa0, v79
	v_add_u32_e32 v62, 0xffffff9d, v79
	v_add_u32_e32 v63, 0xffffff9e, v79
	v_cvt_f32_i32_e32 v60, v60
	v_cvt_f32_i32_e32 v64, v61
	v_cvt_f32_i32_e32 v62, v62
	v_cvt_f32_i32_e32 v65, v63
	v_xor_b32_e32 v61, 0x80000000, v60
	v_xor_b32_e32 v60, 0x80000000, v64
	v_xor_b32_e32 v63, 0x80000000, v62
	v_xor_b32_e32 v62, 0x80000000, v65
	v_add_u32_e32 v64, 0xffffff8f, v79
	v_add_u32_e32 v65, 0xffffff90, v79
	v_add_u32_e32 v66, 0xffffff8d, v79
	v_add_u32_e32 v67, 0xffffff8e, v79
	v_cvt_f32_i32_e32 v64, v64
	v_cvt_f32_i32_e32 v68, v65
	v_cvt_f32_i32_e32 v66, v66
	v_cvt_f32_i32_e32 v69, v67
	s_lshl_b32 s43, s46, 14
	s_mov_b64 s[82:83], s[72:73]
	s_mov_b64 s[72:73], s[64:65]
	v_bfi_b32 v127, -16, s15, v152
	s_sub_i32 s64, s51, 64
	s_add_i32 s15, s63, 0xffffff60
	s_add_i32 s88, s43, s30
	v_readlane_b32 s2, v255, 42
	v_xor_b32_e32 v65, 0x80000000, v64
	v_xor_b32_e32 v64, 0x80000000, v68
	v_or_b32_e32 v68, 0xffffff80, v79
	s_add_u32 s42, s2, s42
	v_readlane_b32 s2, v255, 43
	s_mulk_i32 s51, 0xa0
	v_xor_b32_e32 v67, 0x80000000, v66
	v_xor_b32_e32 v66, 0x80000000, v69
	v_cvt_f32_i32_e32 v90, v68
	v_add_u32_e32 v68, 0xffffff7f, v79
	v_add_u32_e32 v69, 0xffffff7e, v79
	v_lshlrev_b32_e32 v40, 3, v46
	v_mov_b32_e32 v41, v2
	s_addc_u32 s43, s2, 0
	s_add_i32 s65, s51, 0
	v_mul_f32_e32 v37, 0xbfb8aa3b, v37
	v_cvt_f32_i32_e32 v73, v69
	v_cvt_f32_i32_e32 v72, v68
	v_lshl_add_u64 v[116:117], s[44:45], 0, v[42:43]
	v_lshl_add_u64 v[118:119], s[42:43], 0, v[40:41]
	v_mul_f32_e32 v70, v44, v37
	v_add_u32_e32 v77, s65, v42
	v_subrev_u32_e32 v40, 18, v79
	v_subrev_u32_e32 v42, 19, v79
	v_add_u32_e32 v44, -16, v79
	v_add_u32_e32 v68, 0xffffff7d, v79
	v_cmp_eq_u32_e64 s[42:43], 0, v46
	v_mul_u32_u24_e32 v78, 0xa0, v45
	v_add_u32_e32 v37, -1, v79
	v_add_u32_e32 v88, -2, v79
	v_add_u32_e32 v89, -3, v79
	v_subrev_u32_e32 v41, 17, v79
	v_cvt_f32_u32_e32 v43, v42
	v_cvt_f32_u32_e32 v42, v40
	v_cvt_f32_u32_e32 v40, v44
	v_subrev_u32_e32 v46, 34, v79
	v_subrev_u32_e32 v47, 35, v79
	v_subrev_u32_e32 v44, 32, v79
	v_subrev_u32_e32 v45, 33, v79
	v_subrev_u32_e32 v49, 49, v79
	v_cvt_f32_i32_e32 v91, v68
	s_movk_i32 s2, 0x41
	v_cvt_f32_u32_e32 v37, v37
	v_cvt_f32_u32_e32 v39, v89
	v_cvt_f32_u32_e32 v38, v88
	v_cvt_f32_u32_e32 v41, v41
	v_cvt_f32_u32_e32 v45, v45
	v_cvt_f32_u32_e32 v44, v44
	v_cvt_f32_u32_e32 v47, v47
	v_cvt_f32_u32_e32 v46, v46
	v_cvt_f32_u32_e32 v49, v49
	v_cmp_gt_u32_e64 s[44:45], s2, v79
	v_cmp_gt_u32_e64 s[48:49], s2, v88
	v_cmp_gt_u32_e64 s[50:51], s2, v89
	s_mov_b32 s2, 0xc2800000
	v_pk_mul_f32 v[74:75], v[70:71], v[72:73] op_sel_hi:[0,1] neg_lo:[0,1] neg_hi:[0,1]
	v_cmp_le_f32_e64 s[54:55], s2, v72
	v_bfe_u32 v72, v152, 2, 2
	v_lshlrev_b32_e32 v76, 3, v152
	v_or_b32_e32 v72, v128, v72
	v_cvt_f32_ubyte0_e32 v36, v79
	s_movk_i32 s46, 0x42
	v_cmp_le_f32_e64 s[52:53], s2, v90
	v_cmp_le_f32_e64 s[56:57], s2, v73
	v_cmp_le_f32_e64 s[58:59], s2, v91
	v_and_b32_e32 v73, 24, v76
	v_mul_u32_u24_e32 v72, 0xa0, v72
	s_lshl_b32 s14, s14, 2
	v_readlane_b32 s2, v255, 44
	v_pk_mul_f32 v[38:39], v[70:71], v[38:39] op_sel_hi:[0,1]
	v_pk_mul_f32 v[36:37], v[70:71], v[36:37] op_sel_hi:[0,1]
	v_pk_mul_f32 v[42:43], v[70:71], v[42:43] op_sel_hi:[0,1]
	v_pk_mul_f32 v[40:41], v[70:71], v[40:41] op_sel_hi:[0,1]
	v_pk_mul_f32 v[46:47], v[70:71], v[46:47] op_sel_hi:[0,1]
	v_pk_mul_f32 v[44:45], v[70:71], v[44:45] op_sel_hi:[0,1]
	v_pk_mul_f32 v[50:51], v[70:71], v[50:51] op_sel_hi:[0,1]
	v_pk_mul_f32 v[48:49], v[70:71], v[48:49] op_sel_hi:[0,1]
	v_pk_mul_f32 v[54:55], v[70:71], v[54:55] op_sel_hi:[0,1]
	v_pk_mul_f32 v[52:53], v[70:71], v[52:53] op_sel_hi:[0,1]
	v_pk_mul_f32 v[58:59], v[70:71], v[58:59] op_sel_hi:[0,1]
	v_pk_mul_f32 v[56:57], v[70:71], v[56:57] op_sel_hi:[0,1]
	v_pk_mul_f32 v[62:63], v[70:71], v[62:63] op_sel_hi:[0,1]
	v_pk_mul_f32 v[60:61], v[70:71], v[60:61] op_sel_hi:[0,1]
	v_pk_mul_f32 v[66:67], v[70:71], v[66:67] op_sel_hi:[0,1]
	v_pk_mul_f32 v[64:65], v[70:71], v[64:65] op_sel_hi:[0,1]
	v_mul_f32_e64 v68, v70, -v90
	v_mul_f32_e64 v71, v70, -v91
	v_mov_b32_e32 v69, v74
	v_mov_b32_e32 v70, v75
	v_cmp_gt_u32_e64 s[46:47], s46, v79
	v_add3_u32 v129, s65, v73, v72
	s_add_u32 s90, s2, s14
	v_readlane_b32 s2, v255, 45
	v_add_u32_e32 v130, v77, v78
	s_waitcnt vmcnt(0)
	v_mov_b64_e32 v[72:73], v[84:85]
	v_mov_b64_e32 v[76:77], v[80:81]
	s_mov_b64 s[12:13], s[76:77]
	s_mov_b64 s[76:77], s[68:69]
	s_mov_b32 s87, 0
	s_mov_b32 s89, s31
	s_addc_u32 s91, s2, 0
	v_mov_b64_e32 v[74:75], v[86:87]
	v_mov_b64_e32 v[78:79], v[82:83]
	ds_write_b128 v123, v[4:7]
	ds_write_b128 v123, v[8:11] offset:40960
	ds_write_b128 v124, v[12:15]
	ds_write_b128 v124, v[16:19] offset:40960
	ds_write_b128 v125, v[20:23]
	ds_write_b128 v125, v[24:27] offset:40960
	ds_write_b128 v126, v[28:31]
	ds_write_b128 v126, v[32:35] offset:40960
	s_waitcnt lgkmcnt(0)
	s_barrier
	s_branch .LBB0_171

; __device__ __forceinline__ unsigned pk2(float lo, float hi) { f32x2 v = {lo, hi}; bf16x2_t b = __builtin_convertvector(v, bf16x2_t); return __builtin_bit_cast(unsigned, b); }
; __device__ __forceinline__ float flog2(float x) { return __builtin_amdgcn_logf(x); }
; __device__ __forceinline__ float frcp(float x) { return __builtin_amdgcn_rcpf(x); }
; __device__ __forceinline__ float xsum16(float x) { auto r = __builtin_amdgcn_permlane16_swap(__float_as_uint(x), __float_as_uint(x), false, false); return __uint_as_float(r[0]) + __uint_as_float(r[1]); }
; __device__ __forceinline__ float xsum32(float x) { auto r = __builtin_amdgcn_permlane32_swap(__float_as_uint(x), __float_as_uint(x), false, false); return __uint_as_float(r[0]) + __uint_as_float(r[1]); }
; __device__ __forceinline__ void dil_unit(LAS unsigned char* lds, const bf16_t* zB, bf16_t* OP, float* LSE, int bl, int h, int pi, int su, float slope, int tid) {
;     ...
;         l = xsum32(xsum16(l));
;         const float il = frcp(l);
;         const size_t qrow = rb + (size_t)((m0 + wv * 16 + fr) * d + r);
;         bf16_t* op = OP + ((size_t)pi * MH + qrow) * 512 + h * 64 + quad * 4;
; #pragma unroll
;         for (int t = 0; t < 4; ++t) { u32x2 w; w.x = pk2(o[t][0] * il, o[t][1] * il); w.y = pk2(o[t][2] * il, o[t][3] * il); *(u32x2*)(op + t * 16) = w; }
;         if (quad == 0) LSE[((size_t)pi * MH + qrow) * 8 + h] = m + flog2(l);
.LBB0_177:
	v_mov_b32_e32 v80, v104
	s_nop 1
	v_permlane16_swap_b32_e32 v104, v80
	v_add_f32_e32 v80, v104, v80
	v_mov_b32_e32 v81, v80
	s_nop 1
	v_permlane32_swap_b32_e32 v80, v81
	v_add_f32_e32 v82, v80, v81
	v_add_u32_e32 v80, s69, v127
	s_lshr_b32 s14, s68, s84
	v_rcp_f32_e32 v84, v82
	v_lshlrev_b32_e32 v80, s62, v80
	v_add_u32_e32 v80, s14, v80
	v_ashrrev_i32_e32 v81, 31, v80
	v_lshl_add_u64 v[80:81], v[80:81], 0, s[88:89]
	v_lshlrev_b64 v[86:87], 10, v[80:81]
	v_pk_mul_f32 v[88:89], v[88:89], v[84:85] op_sel_hi:[1,0]
	v_pk_mul_f32 v[90:91], v[90:91], v[84:85] op_sel_hi:[1,0]
	v_lshl_add_u64 v[86:87], v[118:119], 0, v[86:87]
	v_cvt_pk_bf16_f32 v88, v88, v89
	v_cvt_pk_bf16_f32 v89, v90, v91
	global_store_dwordx2 v[86:87], v[88:89], off sc1
	v_pk_mul_f32 v[88:89], v[92:93], v[84:85] op_sel_hi:[1,0]
	v_pk_mul_f32 v[90:91], v[94:95], v[84:85] op_sel_hi:[1,0]
	v_cvt_pk_bf16_f32 v88, v88, v89
	v_cvt_pk_bf16_f32 v89, v90, v91
	global_store_dwordx2 v[86:87], v[88:89], off offset:32 sc1
	v_pk_mul_f32 v[88:89], v[96:97], v[84:85] op_sel_hi:[1,0]
	v_pk_mul_f32 v[90:91], v[98:99], v[84:85] op_sel_hi:[1,0]
	v_cvt_pk_bf16_f32 v88, v88, v89
	v_cvt_pk_bf16_f32 v89, v90, v91
	global_store_dwordx2 v[86:87], v[88:89], off offset:64 sc1
	v_pk_mul_f32 v[88:89], v[100:101], v[84:85] op_sel_hi:[1,0]
	v_pk_mul_f32 v[84:85], v[102:103], v[84:85] op_sel_hi:[1,0]
	v_cvt_pk_bf16_f32 v88, v88, v89
	v_cvt_pk_bf16_f32 v89, v84, v85
	global_store_dwordx2 v[86:87], v[88:89], off offset:96 sc1
	s_and_saveexec_b64 s[94:95], s[42:43]
	s_cbranch_execz .LBB0_179
	v_log_f32_e32 v82, v82
	v_lshlrev_b64 v[80:81], 5, v[80:81]
	v_lshl_add_u64 v[80:81], s[90:91], 0, v[80:81]
	v_add_f32_e32 v82, v131, v82
	global_store_dword v[80:81], v82, off sc1

; #define LAS __attribute__((address_space(3)))
; __device__ __forceinline__ f32x4 mfma16(bf16x8 a, bf16x8 b, f32x4 c) { return __builtin_amdgcn_mfma_f32_16x16x32_bf16(a, b, c, 0, 0, 0); }
; __device__ __forceinline__ s16x4 ldtr(const LAS unsigned char* p) { return __builtin_bit_cast(s16x4, __builtin_amdgcn_ds_read_tr16_b64_v4i16((LAS v4i16_t*)p)); }
; __device__ __forceinline__ void hgrn_unit(LAS unsigned char* lds, bf16_t* zC, int bl, int h, int dir, float lb, int tid, bf16_t* ob, int ostr, int ocol) {
;     ...
; #pragma unroll
;         for (int sb = 0; sb < 2; ++sb) {
;             f32x4 at[2][4];
; #pragma unroll
;             for (int ts = 0; ts < 2; ++ts)
; #pragma unroll
;                 for (int tt = 0; tt < 4; ++tt) at[ts][tt] = (f32x4){0.f, 0.f, 0.f, 0.f};
; #pragma unroll
;             for (int ks = 0; ks < 4; ++ks) {
;                 bf16x8 qf[4];
; #pragma unroll
;                 for (int tt = 0; tt < 4; ++tt) if (tt >= 2 * sb) qf[tt] = *(const LAS bf16x8*)(lds + HG_QE + (tt * 16 + fr) * 272 + (ks * 32 + quad * 8) * 2);
;                 if (sb == 0) {
;                     const bf16x8 sa = *(const LAS bf16x8*)(lds + HG_STB + (wv * 16 + fr) * 272 + (ks * 32 + quad * 8) * 2);
; #pragma unroll
;                     for (int tt = 0; tt < 4; ++tt) o[tt] = mfma16(sa, qf[tt], o[tt]);
;                 }
; #pragma unroll
;                 for (int ts = 0; ts < 2; ++ts) {
;                     const int a = sb * 2 + ts;
;                     const bf16x8 kf = *(const LAS bf16x8*)(lds + HG_KN + (a * 16 + fr) * 272 + (ks * 32 + quad * 8) * 2);
; #pragma unroll
;                     for (int tt = 0; tt < 4; ++tt) if (tt >= a) at[ts][tt] = mfma16(kf, qf[tt], at[ts][tt]);
;                 }
;             }
; #pragma unroll
;             for (int ts = 0; ts < 2; ++ts)
; #pragma unroll
;                 for (int j = 0; j < 4; ++j) at[ts][sb * 2 + ts][j] = (quad * 4 + j > fr) ? 0.f : at[ts][sb * 2 + ts][j];
;             const LAS unsigned char* vp = lds + HG_VV + (sb * 32 + quad * 4 + (fr >> 2)) * 288 + (wv * 16 + (fr & 3) * 4) * 2;
;             const bf16x8 vf = cat8(ldtr(vp), ldtr(vp + 16 * 288));
; #pragma unroll
;             for (int tt = 0; tt < 4; ++tt) if (tt >= 2 * sb) o[tt] = mfma16(vf, pack8(at[0][tt], at[1][tt]), o[tt]);
.LBB0_193:
	ds_read_b128 v[60:63], v112
	ds_read_b128 v[64:67], v112 offset:4352
	ds_read_b128 v[72:75], v112 offset:8704
	ds_read_b128 v[68:71], v112 offset:13056
	ds_read_b128 v[76:79], v113
	ds_read_b128 v[126:129], v112 offset:17408
	ds_read_b128 v[144:147], v112 offset:21760
	ds_read_b128 v[156:159], v112 offset:64
	ds_read_b128 v[160:163], v112 offset:4416
	ds_read_b128 v[164:167], v112 offset:8768
	ds_read_b128 v[168:171], v112 offset:13120
	ds_read_b128 v[188:191], v113 offset:64
	v_subrev_u32_e32 v102, 64, v102
	s_waitcnt lgkmcnt(7)
	v_mfma_f32_16x16x32_bf16 v[80:83], v[76:79], v[60:63], 0
	v_subrev_u32_e32 v104, 64, v104
	v_mfma_f32_16x16x32_bf16 v[118:121], v[76:79], v[64:67], 0
	v_mfma_f32_16x16x32_bf16 v[122:125], v[76:79], v[72:75], 0
	v_mfma_f32_16x16x32_bf16 v[76:79], v[76:79], v[68:71], 0
	s_waitcnt lgkmcnt(0)
	v_mfma_f32_16x16x32_bf16 v[80:83], v[188:191], v[156:159], v[80:83]
	v_mfma_f32_16x16x32_bf16 v[118:121], v[188:191], v[160:163], v[118:121]
	v_mfma_f32_16x16x32_bf16 v[122:125], v[188:191], v[164:167], v[122:125]
	v_mfma_f32_16x16x32_bf16 v[76:79], v[188:191], v[168:171], v[76:79]
	ds_read_b128 v[188:191], v112 offset:17472
	v_mfma_f32_16x16x32_bf16 v[60:63], v[126:129], v[60:63], 0
	s_waitcnt lgkmcnt(0)
	v_mfma_f32_16x16x32_bf16 v[60:63], v[188:191], v[156:159], v[60:63]
	ds_read_b128 v[156:159], v112 offset:21824
	v_mfma_f32_16x16x32_bf16 v[130:133], v[126:129], v[64:67], 0
	v_mfma_f32_16x16x32_bf16 v[134:137], v[126:129], v[72:75], 0
	v_mfma_f32_16x16x32_bf16 v[126:129], v[126:129], v[68:71], 0
	v_mfma_f32_16x16x32_bf16 v[64:67], v[144:147], v[64:67], 0
	v_mfma_f32_16x16x32_bf16 v[152:155], v[144:147], v[72:75], 0
	v_mfma_f32_16x16x32_bf16 v[144:147], v[144:147], v[68:71], 0
	v_mfma_f32_16x16x32_bf16 v[130:133], v[188:191], v[160:163], v[130:133]
	v_mfma_f32_16x16x32_bf16 v[134:137], v[188:191], v[164:167], v[134:137]
	v_mfma_f32_16x16x32_bf16 v[126:129], v[188:191], v[168:171], v[126:129]
	s_waitcnt lgkmcnt(0)
	v_mfma_f32_16x16x32_bf16 v[64:67], v[156:159], v[160:163], v[64:67]
	v_mfma_f32_16x16x32_bf16 v[152:155], v[156:159], v[164:167], v[152:155]
	v_mfma_f32_16x16x32_bf16 v[144:147], v[156:159], v[168:171], v[144:147]
	ds_read_b128 v[156:159], v112 offset:128
	ds_read_b128 v[160:163], v112 offset:4480
	ds_read_b128 v[164:167], v112 offset:8832
	ds_read_b128 v[168:171], v112 offset:13184
	ds_read_b128 v[188:191], v113 offset:128
	s_waitcnt lgkmcnt(0)
	v_mfma_f32_16x16x32_bf16 v[80:83], v[188:191], v[156:159], v[80:83]
	v_mfma_f32_16x16x32_bf16 v[118:121], v[188:191], v[160:163], v[118:121]
	v_mfma_f32_16x16x32_bf16 v[122:125], v[188:191], v[164:167], v[122:125]
	v_mfma_f32_16x16x32_bf16 v[76:79], v[188:191], v[168:171], v[76:79]
	ds_read_b128 v[188:191], v112 offset:17536
	s_waitcnt lgkmcnt(0)
	v_mfma_f32_16x16x32_bf16 v[60:63], v[188:191], v[156:159], v[60:63]
	ds_read_b128 v[156:159], v112 offset:21888
	v_mfma_f32_16x16x32_bf16 v[130:133], v[188:191], v[160:163], v[130:133]
	v_mfma_f32_16x16x32_bf16 v[134:137], v[188:191], v[164:167], v[134:137]
	v_mfma_f32_16x16x32_bf16 v[126:129], v[188:191], v[168:171], v[126:129]
	s_waitcnt lgkmcnt(0)
	v_mfma_f32_16x16x32_bf16 v[64:67], v[156:159], v[160:163], v[64:67]
	v_mfma_f32_16x16x32_bf16 v[152:155], v[156:159], v[164:167], v[152:155]
	v_mfma_f32_16x16x32_bf16 v[144:147], v[156:159], v[168:171], v[144:147]
	ds_read_b128 v[156:159], v112 offset:192
	ds_read_b128 v[160:163], v112 offset:4544
	ds_read_b128 v[164:167], v112 offset:8896
	ds_read_b128 v[168:171], v112 offset:13248
	ds_read_b128 v[188:191], v113 offset:192
	s_waitcnt lgkmcnt(0)
	v_mfma_f32_16x16x32_bf16 v[80:83], v[188:191], v[156:159], v[80:83]
	v_mfma_f32_16x16x32_bf16 v[118:121], v[188:191], v[160:163], v[118:121]
	v_mfma_f32_16x16x32_bf16 v[122:125], v[188:191], v[164:167], v[122:125]
	v_mfma_f32_16x16x32_bf16 v[76:79], v[188:191], v[168:171], v[76:79]
	ds_read_b128 v[188:191], v112 offset:17600
	s_waitcnt lgkmcnt(0)
	v_mfma_f32_16x16x32_bf16 v[60:63], v[188:191], v[156:159], v[60:63]
	ds_read_b128 v[156:159], v112 offset:21952
	s_nop 6
	v_cndmask_b32_e64 v0, v60, 0, s[50:51]
	s_waitcnt lgkmcnt(0)
	v_mfma_f32_16x16x32_bf16 v[64:67], v[156:159], v[160:163], v[64:67]
	v_cndmask_b32_e64 v1, 0, v61, s[52:53]
	v_cndmask_b32_e64 v3, v62, 0, s[54:55]
	v_cndmask_b32_e64 v60, v63, 0, s[56:57]
	v_mfma_f32_16x16x32_bf16 v[130:133], v[188:191], v[160:163], v[130:133]
	s_nop 3
	v_cndmask_b32_e64 v138, v64, 0, s[50:51]
	v_cndmask_b32_e64 v139, 0, v65, s[52:53]
	v_cndmask_b32_e64 v140, v66, 0, s[54:55]
	v_mfma_f32_16x16x32_bf16 v[152:155], v[156:159], v[164:167], v[152:155]
	v_cndmask_b32_e64 v141, v67, 0, s[56:57]
	v_cvt_pk_bf16_f32 v0, v0, v1
	v_cvt_pk_bf16_f32 v1, v3, v60
	v_mfma_f32_16x16x32_bf16 v[144:147], v[156:159], v[168:171], v[144:147]
	ds_read_b64_tr_b16 v[156:157], v97 offset:53248
	ds_read_b64_tr_b16 v[158:159], v97 offset:57856
	v_mov_b32_e32 v3, v2
	v_cvt_pk_bf16_f32 v60, v130, v131
	v_mfma_f32_16x16x32_bf16 v[134:137], v[188:191], v[164:167], v[134:137]
	v_cvt_pk_bf16_f32 v61, v132, v133
	v_cvt_pk_bf16_f32 v62, v138, v139
	v_cvt_pk_bf16_f32 v63, v140, v141
	v_mfma_f32_16x16x32_bf16 v[126:129], v[188:191], v[168:171], v[126:129]
	s_waitcnt lgkmcnt(0)
	v_mfma_f32_16x16x32_bf16 v[64:67], v[156:159], v[0:3], v[80:83]
	v_mfma_f32_16x16x32_bf16 v[60:63], v[156:159], v[60:63], v[118:121]
	s_nop 1
	v_cvt_pk_bf16_f32 v80, v134, v135
	v_cvt_pk_bf16_f32 v81, v136, v137
	v_cvt_pk_bf16_f32 v82, v152, v153
	v_cvt_pk_bf16_f32 v83, v154, v155
	v_cvt_pk_bf16_f32 v118, v126, v127
	v_cvt_pk_bf16_f32 v119, v128, v129
	v_cvt_pk_bf16_f32 v120, v144, v145
	v_cvt_pk_bf16_f32 v121, v146, v147
	v_mfma_f32_16x16x32_bf16 v[80:83], v[156:159], v[80:83], v[122:125]
	s_nop 0
	v_mfma_f32_16x16x32_bf16 v[76:79], v[156:159], v[118:121], v[76:79]
	ds_read_b128 v[118:121], v114 offset:17408
	ds_read_b128 v[122:125], v114 offset:21760
	s_waitcnt lgkmcnt(1)
; #define LAS __attribute__((address_space(3)))
; __device__ __forceinline__ unsigned pk2(float lo, float hi) { f32x2 v = {lo, hi}; bf16x2_t b = __builtin_convertvector(v, bf16x2_t); return __builtin_bit_cast(unsigned, b); }
; __device__ __forceinline__ f32x4 mfma16(bf16x8 a, bf16x8 b, f32x4 c) { return __builtin_amdgcn_mfma_f32_16x16x32_bf16(a, b, c, 0, 0, 0); }
; __device__ __forceinline__ s16x4 ldtr(const LAS unsigned char* p) { return __builtin_bit_cast(s16x4, __builtin_amdgcn_ds_read_tr16_b64_v4i16((LAS v4i16_t*)p)); }
; __device__ __forceinline__ void hgrn_unit(LAS unsigned char* lds, bf16_t* zC, int bl, int h, int dir, float lb, int tid, bf16_t* ob, int ostr, int ocol) {
;     ...
;                     for (int tt = 0; tt < 4; ++tt) if (tt >= a) at[ts][tt] = mfma16(kf, qf[tt], at[ts][tt]);
;                 }
;             }
; #pragma unroll
;             for (int ts = 0; ts < 2; ++ts)
; #pragma unroll
;                 for (int j = 0; j < 4; ++j) at[ts][sb * 2 + ts][j] = (quad * 4 + j > fr) ? 0.f : at[ts][sb * 2 + ts][j];
;             const LAS unsigned char* vp = lds + HG_VV + (sb * 32 + quad * 4 + (fr >> 2)) * 288 + (wv * 16 + (fr & 3) * 4) * 2;
;             const bf16x8 vf = cat8(ldtr(vp), ldtr(vp + 16 * 288));
; #pragma unroll
;             for (int tt = 0; tt < 4; ++tt) if (tt >= 2 * sb) o[tt] = mfma16(vf, pack8(at[0][tt], at[1][tt]), o[tt]);
;         }
; #pragma unroll
;         for (int kt = 0; kt < 8; ++kt) { const float eb = ((const LAS float*)(lds + HG_EBT))[kt * 16 + fr]; st[kt] = st[kt] * eb; }
; #pragma unroll
;         for (int tb = 0; tb < 2; ++tb) {
;             const LAS unsigned char* vp = lds + HG_VV + (tb * 32 + quad * 8 + (fr >> 2)) * 288 + (wv * 16 + (fr & 3) * 4) * 2;
;             const bf16x8 vf = cat8(ldtr(vp), ldtr(vp + 4 * 288));
; #pragma unroll
;             for (int kt = 0; kt < 8; ++kt) { const bf16x8 kb = *(const LAS bf16x8*)(lds + HG_KET + (kt * 16 + fr) * 144 + (tb * 32 + quad * 8) * 2); st[kt] = mfma16(vf, kb, st[kt]); }
;         }
; #pragma unroll
;         for (int tt = 0; tt < 4; ++tt) { u32x2 w; w.x = pk2(o[tt][0], o[tt][1]); w.y = pk2(o[tt][2], o[tt][3]);
;             *(u32x2*)(ob + (size_t)hg_row(bl, dir, c, tt * 16 + fr) * ostr + ocol + wv * 16 + quad * 4) = w; }
	v_mfma_f32_16x16x32_bf16 v[72:75], v[118:121], v[72:75], 0
	v_mfma_f32_16x16x32_bf16 v[118:121], v[118:121], v[68:71], 0
	s_waitcnt lgkmcnt(0)
	v_mfma_f32_16x16x32_bf16 v[68:71], v[122:125], v[68:71], 0
	ds_read_b128 v[122:125], v114 offset:64
	ds_read_b128 v[126:129], v114 offset:4416
	ds_read_b128 v[130:133], v114 offset:17472
	s_waitcnt lgkmcnt(0)
	v_mfma_f32_16x16x32_bf16 v[72:75], v[130:133], v[122:125], v[72:75]
	ds_read_b128 v[122:125], v114 offset:21824
	v_mfma_f32_16x16x32_bf16 v[118:121], v[130:133], v[126:129], v[118:121]
	s_waitcnt lgkmcnt(0)
	v_mfma_f32_16x16x32_bf16 v[68:71], v[122:125], v[126:129], v[68:71]
	ds_read_b128 v[122:125], v114 offset:128
	ds_read_b128 v[126:129], v114 offset:4480
	ds_read_b128 v[130:133], v114 offset:17536
	s_waitcnt lgkmcnt(0)
	v_mfma_f32_16x16x32_bf16 v[72:75], v[130:133], v[122:125], v[72:75]
	ds_read_b128 v[122:125], v114 offset:21888
	v_mfma_f32_16x16x32_bf16 v[118:121], v[130:133], v[126:129], v[118:121]
	s_waitcnt lgkmcnt(0)
	v_mfma_f32_16x16x32_bf16 v[122:125], v[122:125], v[126:129], v[68:71]
	s_nop 2
	ds_read_b128 v[68:71], v114 offset:192
	ds_read_b128 v[126:129], v114 offset:4544
	ds_read_b128 v[130:133], v114 offset:17600
	s_waitcnt lgkmcnt(0)
	v_mfma_f32_16x16x32_bf16 v[72:75], v[130:133], v[68:71], v[72:75]
	v_mfma_f32_16x16x32_bf16 v[68:71], v[130:133], v[126:129], v[118:121]
	s_nop 6
	v_cndmask_b32_e64 v0, v72, 0, s[50:51]
	v_cndmask_b32_e64 v1, 0, v73, s[52:53]
	v_cndmask_b32_e64 v3, v74, 0, s[54:55]
	ds_read_b128 v[118:121], v114 offset:21952
	s_waitcnt lgkmcnt(0)
	v_mfma_f32_16x16x32_bf16 v[118:121], v[118:121], v[126:129], v[122:125]
	v_cndmask_b32_e64 v72, v75, 0, s[56:57]
	v_cvt_pk_bf16_f32 v0, v0, v1
	v_cvt_pk_bf16_f32 v1, v3, v72
	s_nop 4
	v_cndmask_b32_e64 v122, v118, 0, s[50:51]
	v_cndmask_b32_e64 v123, 0, v119, s[52:53]
	v_cndmask_b32_e64 v124, v120, 0, s[54:55]
	v_cndmask_b32_e64 v125, v121, 0, s[56:57]
	ds_read_b64_tr_b16 v[118:119], v97 offset:62464
	ds_read_b64_tr_b16 v[120:121], v98 offset:13824
	v_mov_b32_e32 v3, v2
	v_cvt_pk_bf16_f32 v68, v68, v69
	v_cvt_pk_bf16_f32 v69, v70, v71
	s_waitcnt lgkmcnt(0)
	v_mfma_f32_16x16x32_bf16 v[72:75], v[118:121], v[0:3], v[80:83]
	ds_read2_b32 v[126:127], v95 offset1:16
	ds_read2_b32 v[128:129], v95 offset0:32 offset1:48
	ds_read2_b32 v[132:133], v95 offset0:64 offset1:80
	ds_read2_b32 v[134:135], v95 offset0:96 offset1:112
	ds_read_b64_tr_b16 v[152:153], v115 offset:53248
	ds_read_b64_tr_b16 v[154:155], v115 offset:54400
	v_add_u32_e32 v136, v94, v99
	v_cvt_pk_bf16_f32 v70, v122, v123
	v_cvt_pk_bf16_f32 v71, v124, v125
	ds_read_b128 v[192:195], v136 offset:34816
	ds_read_b128 v[196:199], v136 offset:37120
	ds_read_b128 v[200:203], v136 offset:39424
	ds_read_b128 v[204:207], v136 offset:41728
	ds_read_b128 v[208:211], v136 offset:44032
	ds_read_b128 v[212:215], v136 offset:46336
	ds_read_b128 v[216:219], v136 offset:48640
	ds_read_b128 v[220:223], v136 offset:50944
	v_add_u32_e32 v3, s63, v91
	s_add_i32 s63, s63, 64
	v_mfma_f32_16x16x32_bf16 v[68:71], v[118:121], v[68:71], v[76:79]
	v_cvt_pk_bf16_f32 v138, v64, v65
	v_cvt_pk_bf16_f32 v139, v66, v67
	v_add_u32_e32 v172, 48, v100
	v_cndmask_b32_e32 v172, v172, v3, vcc
	v_add_u32_e32 v172, s62, v172
	v_mad_i64_i32 v[144:145], s[14:15], v172, s8, v[88:89]
	v_cvt_pk_bf16_f32 v140, v60, v61
	v_cvt_pk_bf16_f32 v141, v62, v63
	v_add_u32_e32 v172, 16, v3
	v_add_u32_e32 v173, 32, v100
	v_cndmask_b32_e32 v172, v173, v172, vcc
	v_add_u32_e32 v172, s62, v172
	global_store_dwordx2 v[144:145], v[138:139], off sc1
	v_mad_i64_i32 v[146:147], s[14:15], v172, s8, v[88:89]
	v_cvt_pk_bf16_f32 v142, v72, v73
	v_cvt_pk_bf16_f32 v143, v74, v75
	v_add_u32_e32 v172, 32, v3
	v_add_u32_e32 v173, 16, v100
	v_cndmask_b32_e32 v172, v173, v172, vcc
	v_add_u32_e32 v172, s62, v172
	global_store_dwordx2 v[146:147], v[140:141], off sc1
	v_mad_i64_i32 v[168:169], s[14:15], v172, s8, v[88:89]
	v_add_u32_e32 v3, 48, v3
	v_cndmask_b32_e32 v3, v100, v3, vcc
	v_add_u32_e32 v3, s62, v3
	global_store_dwordx2 v[168:169], v[142:143], off sc1
	v_mad_i64_i32 v[170:171], s[14:15], v3, s8, v[88:89]
	v_subrev_u32_e32 v100, 64, v100
	s_waitcnt lgkmcnt(10)
; #define LAS __attribute__((address_space(3)))
; __device__ __forceinline__ unsigned pk2(float lo, float hi) { f32x2 v = {lo, hi}; bf16x2_t b = __builtin_convertvector(v, bf16x2_t); return __builtin_bit_cast(unsigned, b); }
; __device__ __forceinline__ f32x4 mfma16(bf16x8 a, bf16x8 b, f32x4 c) { return __builtin_amdgcn_mfma_f32_16x16x32_bf16(a, b, c, 0, 0, 0); }
; __device__ __forceinline__ s16x4 ldtr(const LAS unsigned char* p) { return __builtin_bit_cast(s16x4, __builtin_amdgcn_ds_read_tr16_b64_v4i16((LAS v4i16_t*)p)); }
; __device__ __forceinline__ void hgrn_unit(LAS unsigned char* lds, bf16_t* zC, int bl, int h, int dir, float lb, int tid, bf16_t* ob, int ostr, int ocol) {
;     ...
; #pragma unroll
;         for (int kt = 0; kt < 8; ++kt) { const float eb = ((const LAS float*)(lds + HG_EBT))[kt * 16 + fr]; st[kt] = st[kt] * eb; }
; #pragma unroll
;         for (int tb = 0; tb < 2; ++tb) {
;             const LAS unsigned char* vp = lds + HG_VV + (tb * 32 + quad * 8 + (fr >> 2)) * 288 + (wv * 16 + (fr & 3) * 4) * 2;
;             const bf16x8 vf = cat8(ldtr(vp), ldtr(vp + 4 * 288));
; #pragma unroll
;             for (int kt = 0; kt < 8; ++kt) { const bf16x8 kb = *(const LAS bf16x8*)(lds + HG_KET + (kt * 16 + fr) * 144 + (tb * 32 + quad * 8) * 2); st[kt] = mfma16(vf, kb, st[kt]); }
;         }
; #pragma unroll
;         for (int tt = 0; tt < 4; ++tt) { u32x2 w; w.x = pk2(o[tt][0], o[tt][1]); w.y = pk2(o[tt][2], o[tt][3]);
;             *(u32x2*)(ob + (size_t)hg_row(bl, dir, c, tt * 16 + fr) * ostr + ocol + wv * 16 + quad * 4) = w; }
;         __syncthreads();
	v_pk_mul_f32 v[6:7], v[6:7], v[126:127] op_sel_hi:[1,0]
	v_pk_mul_f32 v[4:5], v[4:5], v[126:127] op_sel_hi:[1,0]
	v_mov_b32_e32 v126, v127
	v_pk_mul_f32 v[58:59], v[58:59], v[126:127] op_sel_hi:[1,0]
	v_pk_mul_f32 v[56:57], v[56:57], v[126:127] op_sel_hi:[1,0]
	v_pk_mul_f32 v[50:51], v[50:51], v[128:129] op_sel_hi:[1,0]
	v_pk_mul_f32 v[48:49], v[48:49], v[128:129] op_sel_hi:[1,0]
	v_mov_b32_e32 v128, v129
	v_pk_mul_f32 v[54:55], v[54:55], v[128:129] op_sel_hi:[1,0]
	v_pk_mul_f32 v[52:53], v[52:53], v[128:129] op_sel_hi:[1,0]
	v_pk_mul_f32 v[42:43], v[42:43], v[132:133] op_sel_hi:[1,0]
	v_pk_mul_f32 v[40:41], v[40:41], v[132:133] op_sel_hi:[1,0]
	v_mov_b32_e32 v132, v133
	v_pk_mul_f32 v[46:47], v[46:47], v[132:133] op_sel_hi:[1,0]
	v_pk_mul_f32 v[44:45], v[44:45], v[132:133] op_sel_hi:[1,0]
	v_pk_mul_f32 v[38:39], v[38:39], v[134:135] op_sel_hi:[1,0]
	v_pk_mul_f32 v[36:37], v[36:37], v[134:135] op_sel_hi:[1,0]
	v_mov_b32_e32 v134, v135
	v_pk_mul_f32 v[34:35], v[34:35], v[134:135] op_sel_hi:[1,0]
	v_pk_mul_f32 v[32:33], v[32:33], v[134:135] op_sel_hi:[1,0]
	v_cvt_pk_bf16_f32 v148, v68, v69
	v_cvt_pk_bf16_f32 v149, v70, v71
	global_store_dwordx2 v[170:171], v[148:149], off sc1
	s_waitcnt lgkmcnt(7)
	v_mfma_f32_16x16x32_bf16 v[4:7], v[152:155], v[192:195], v[4:7]
	ds_read_b64_tr_b16 v[156:157], v116 offset:53248
	s_waitcnt lgkmcnt(7)
	v_mfma_f32_16x16x32_bf16 v[56:59], v[152:155], v[196:199], v[56:59]
	ds_read_b64_tr_b16 v[158:159], v116 offset:54400
	s_waitcnt lgkmcnt(7)
	v_mfma_f32_16x16x32_bf16 v[48:51], v[152:155], v[200:203], v[48:51]
	ds_read_b128 v[224:227], v117 offset:34816
	s_waitcnt lgkmcnt(7)
	v_mfma_f32_16x16x32_bf16 v[52:55], v[152:155], v[204:207], v[52:55]
	ds_read_b128 v[228:231], v117 offset:37120
	s_waitcnt lgkmcnt(7)
	v_mfma_f32_16x16x32_bf16 v[40:43], v[152:155], v[208:211], v[40:43]
	ds_read_b128 v[232:235], v117 offset:39424
	s_waitcnt lgkmcnt(7)
	v_mfma_f32_16x16x32_bf16 v[44:47], v[152:155], v[212:215], v[44:47]
	ds_read_b128 v[240:243], v117 offset:41728
	s_waitcnt lgkmcnt(7)
	v_mfma_f32_16x16x32_bf16 v[36:39], v[152:155], v[216:219], v[36:39]
	ds_read_b128 v[244:247], v117 offset:44032
	s_waitcnt lgkmcnt(7)
	v_mfma_f32_16x16x32_bf16 v[32:35], v[152:155], v[220:223], v[32:35]
	ds_read_b128 v[248:251], v117 offset:46336
	ds_read_b128 v[160:163], v117 offset:48640
	ds_read_b128 v[164:167], v117 offset:50944
	s_waitcnt lgkmcnt(7)
	v_mfma_f32_16x16x32_bf16 v[4:7], v[156:159], v[224:227], v[4:7]
	s_waitcnt lgkmcnt(6)
	v_mfma_f32_16x16x32_bf16 v[56:59], v[156:159], v[228:231], v[56:59]
	s_waitcnt lgkmcnt(5)
	v_mfma_f32_16x16x32_bf16 v[48:51], v[156:159], v[232:235], v[48:51]
	s_waitcnt lgkmcnt(4)
	v_mfma_f32_16x16x32_bf16 v[52:55], v[156:159], v[240:243], v[52:55]
	s_waitcnt lgkmcnt(3)
	v_mfma_f32_16x16x32_bf16 v[40:43], v[156:159], v[244:247], v[40:43]
	s_waitcnt lgkmcnt(2)
	v_mfma_f32_16x16x32_bf16 v[44:47], v[156:159], v[248:251], v[44:47]
	s_waitcnt lgkmcnt(1)
	v_mfma_f32_16x16x32_bf16 v[36:39], v[156:159], v[160:163], v[36:39]
	s_waitcnt lgkmcnt(0)
	v_mfma_f32_16x16x32_bf16 v[32:35], v[156:159], v[164:167], v[32:35]
	s_cmpk_eq_i32 s63, 0x800
	s_barrier
	s_cbranch_scc1 .LBB0_160

; __device__ __forceinline__ void xcd_barrier(const XcdBarrier& b) {
;     asm volatile("s_waitcnt vmcnt(0)" ::: "memory");
;     __syncthreads();
;     if (threadIdx.x == 0) {
;         unsigned* bar = b.bar;
;         __builtin_amdgcn_s_waitcnt(0);
;         unsigned nloc = b.st[0], nx = b.st[1];
;         if (nloc == 0u) { xcd_barrier_complete(bar, b.x, nloc, nx); b.st[0] = nloc; b.st[1] = nx; }
; __global__ void __launch_bounds__(512, 2) mega_fwd(Args a) {
;     ...
;         if (ph + 1 < ph_hi) { if (ph == ph_lo) grid.sync(); else xcd_barrier(xbar); }
.LBB0_549:
	s_add_i32 s0, s7, 1
	s_cmp_ge_i32 s0, s75
	s_cbranch_scc1 .LBB0_10
	s_cmp_eq_u32 s7, 16
	s_cbranch_scc1 .LBB0_10
	s_mov_b32 s0, 0x8400420
	s_bitcmp1_b32 s0, s7
	s_cbranch_scc1 .LBB0_10
	s_mov_b64 s[0:1], -1
	s_waitcnt vmcnt(0)
	s_waitcnt lgkmcnt(0)
	s_barrier
	s_mov_b64 s[0:1], exec
	v_readlane_b32 s10, v254, 4
	v_readlane_b32 s11, v254, 5
	s_and_b64 s[10:11], s[0:1], s[10:11]
	s_mov_b64 exec, s[10:11]
	s_cbranch_execz .LBB0_603
	v_readlane_b32 s10, v255, 20
	s_waitcnt vmcnt(0) expcnt(0) lgkmcnt(0)
	s_nop 0
	v_mov_b32_e32 v0, s10
	ds_read_b32 v3, v0
	v_readlane_b32 s10, v255, 21
	s_waitcnt lgkmcnt(0)
	v_cmp_ne_u32_e32 vcc, 0, v3
	v_mov_b32_e32 v0, s10
	ds_read_b32 v0, v0
	s_cbranch_vccnz .LBB0_567
	s_mov_b32 s10, 1
	s_branch .LBB0_555

; __global__ void __launch_bounds__(512, 2) mega_fwd(Args a) {
	.amdhsa_kernel _Z8mega_fwd4Args
		.amdhsa_group_segment_fixed_size 0
		.amdhsa_private_segment_fixed_size 0
		.amdhsa_kernarg_size 464
		.amdhsa_user_sgpr_count 2
		.amdhsa_user_sgpr_dispatch_ptr 0
		.amdhsa_user_sgpr_queue_ptr 0
		.amdhsa_user_sgpr_kernarg_segment_ptr 1
		.amdhsa_user_sgpr_dispatch_id 0
		.amdhsa_user_sgpr_kernarg_preload_length 0
		.amdhsa_user_sgpr_kernarg_preload_offset 0
		.amdhsa_user_sgpr_private_segment_size 0
		.amdhsa_uses_dynamic_stack 0
		.amdhsa_enable_private_segment 0
		.amdhsa_system_sgpr_workgroup_id_x 1
		.amdhsa_system_sgpr_workgroup_id_y 0
		.amdhsa_system_sgpr_workgroup_id_z 0
		.amdhsa_system_sgpr_workgroup_info 0
		.amdhsa_system_vgpr_workitem_id 2
		.amdhsa_next_free_vgpr 256
		.amdhsa_next_free_sgpr 102
		.amdhsa_accum_offset 256
		.amdhsa_reserve_vcc 1
		.amdhsa_float_round_mode_32 0
		.amdhsa_float_round_mode_16_64 0
		.amdhsa_float_denorm_mode_32 3
		.amdhsa_float_denorm_mode_16_64 3
		.amdhsa_dx10_clamp 1
		.amdhsa_ieee_mode 1
		.amdhsa_fp16_overflow 0
		.amdhsa_tg_split 0
		.amdhsa_exception_fp_ieee_invalid_op 0
		.amdhsa_exception_fp_denorm_src 0
		.amdhsa_exception_fp_ieee_div_zero 0
		.amdhsa_exception_fp_ieee_overflow 0
		.amdhsa_exception_fp_ieee_underflow 0
		.amdhsa_exception_fp_ieee_inexact 0
		.amdhsa_exception_int_div_zero 0
	.end_amdhsa_kernel

; __global__ void __launch_bounds__(512, 2) mega_fwd(Args a) {
.Lfunc_end0:
	.size	_Z8mega_fwd4Args, .Lfunc_end0-_Z8mega_fwd4Args
	.set _Z8mega_fwd4Args.num_vgpr, 256
	.set _Z8mega_fwd4Args.num_agpr, 0
	.set _Z8mega_fwd4Args.numbered_sgpr, 102
	.set _Z8mega_fwd4Args.num_named_barrier, 0
	.set _Z8mega_fwd4Args.private_seg_size, 0
	.set _Z8mega_fwd4Args.uses_vcc, 1
	.set _Z8mega_fwd4Args.uses_flat_scratch, 0
	.set _Z8mega_fwd4Args.has_dyn_sized_stack, 0
	.set _Z8mega_fwd4Args.has_recursion, 0
	.set _Z8mega_fwd4Args.has_indirect_call, 0

; __global__ void __launch_bounds__(512, 2) mega_fwd(Args a) {
amdhsa.kernels:
  - .agpr_count:     0
    .args:
      - .offset:         0
        .size:           208
        .value_kind:     by_value
      - .offset:         208
        .size:           4
        .value_kind:     hidden_block_count_x
      - .offset:         212
        .size:           4
        .value_kind:     hidden_block_count_y
      - .offset:         216
        .size:           4
        .value_kind:     hidden_block_count_z
      - .offset:         220
        .size:           2
        .value_kind:     hidden_group_size_x
      - .offset:         222
        .size:           2
        .value_kind:     hidden_group_size_y
      - .offset:         224
        .size:           2
        .value_kind:     hidden_group_size_z
      - .offset:         226
        .size:           2
        .value_kind:     hidden_remainder_x
      - .offset:         228
        .size:           2
        .value_kind:     hidden_remainder_y
      - .offset:         230
        .size:           2
        .value_kind:     hidden_remainder_z
      - .offset:         248
        .size:           8
        .value_kind:     hidden_global_offset_x
      - .offset:         256
        .size:           8
        .value_kind:     hidden_global_offset_y
      - .offset:         264
        .size:           8
        .value_kind:     hidden_global_offset_z
      - .offset:         272
        .size:           2
        .value_kind:     hidden_grid_dims
      - .offset:         296
        .size:           8
        .value_kind:     hidden_multigrid_sync_arg
      - .offset:         328
        .size:           4
        .value_kind:     hidden_dynamic_lds_size
    .group_segment_fixed_size: 0
    .kernarg_segment_align: 8
    .kernarg_segment_size: 464
    .language:       OpenCL C
    .language_version:
      - 2
      - 0
    .max_flat_workgroup_size: 512
    .name:           _Z8mega_fwd4Args
    .private_segment_fixed_size: 0
    .sgpr_count:     108
    .sgpr_spill_count: 114
    .symbol:         _Z8mega_fwd4Args.kd
    .uniform_work_group_size: 1
    .uses_dynamic_stack: false
    .vgpr_count:     256
    .vgpr_spill_count: 0
    .wavefront_size: 64
